# phase 1: the ten small lora convT calls rotated onto different workgroups (they all sat on workgroups 0-7, one after another)
# speedup vs baseline: 1.0072x; 1.0072x over previous
.LBB0_22:
	s_lshl_b32 s1, s0, 15
	s_or_b32 s30, s1, s22
	s_lshl_b32 s0, s0, 18
	v_mov_b32_e32 v4, v196
	v_readlane_b32 vcc_hi, v255, 44
	s_sub_i32 s20, s2, vcc_hi
	s_cmp_lt_i32 s20, 0
	s_cselect_b32 vcc_lo, s34, 0
	s_add_i32 s20, s20, vcc_lo
	s_add_i32 vcc_hi, vcc_hi, 4
	s_cmp_ge_u32 vcc_hi, s34
	s_cselect_b32 vcc_lo, s34, 0
	s_sub_i32 vcc_hi, vcc_hi, vcc_lo
	s_nop 0
	v_writelane_b32 v255, vcc_hi, 44
	v_mov_b32_e32 v0, v196
	s_add_u32 s0, s42, s0
	s_addc_u32 s1, s43, 0
	v_readfirstlane_b32 s21, v0
	s_lshl_b32 s20, s20, 1
	s_ashr_i32 s21, s21, 8
	v_mov_b32_e32 v0, v196
	s_add_i32 s21, s21, s20
	s_nop 0
	v_readfirstlane_b32 s20, v0
	s_ashr_i32 s20, s20, 8
	s_sub_i32 s23, s21, s20
	s_cmp_gt_i32 s23, 7
	s_cbranch_scc1 .LBB0_27
	s_lshl_b64 s[20:21], s[30:31], 2
	v_readlane_b32 s4, v254, 43
	v_mov_b32_e32 v0, v196
	v_readlane_b32 s5, v254, 44
	s_add_u32 s20, s4, s20
	s_addc_u32 s21, s5, s21
	v_readfirstlane_b32 s24, v0
	s_ashr_i32 s24, s24, 8
	s_add_i32 s24, s24, s23
	s_min_i32 s24, s24, 7
	s_lshl_b32 s24, s24, 6
	s_ashr_i32 s25, s24, 31
	v_bfe_u32 v43, v4, 6, 2
	s_lshl_b64 s[24:25], s[24:25], 2
	s_add_u32 s24, s20, s24
	v_lshlrev_b32_e32 v0, 2, v4
	v_lshlrev_b32_e32 v6, 9, v43
	s_addc_u32 s25, s21, s25
	v_and_b32_e32 v0, 0xfc, v0
	s_waitcnt vmcnt(15)
	v_or_b32_e32 v10, 0x800, v6
	v_or_b32_e32 v14, 0x1000, v6
	s_waitcnt vmcnt(9)
	v_or_b32_e32 v18, 0x1800, v6
	s_waitcnt vmcnt(2)
	v_or_b32_e32 v26, 0x2800, v6
	v_or_b32_e32 v34, 0x3800, v6
	v_lshl_add_u64 v[2:3], s[24:25], 0, v[0:1]
	s_waitcnt vmcnt(1)
	v_lshlrev_b32_e32 v8, 11, v43
	v_mov_b32_e32 v9, v1
	v_lshlrev_b32_e32 v12, 2, v10
	v_mov_b32_e32 v13, v1
	s_waitcnt vmcnt(0)
	v_lshlrev_b32_e32 v16, 2, v14
	v_mov_b32_e32 v17, v1
	v_lshlrev_b32_e32 v20, 2, v18
	v_mov_b32_e32 v21, v1
	v_or_b32_e32 v22, 0x2000, v6
	v_lshlrev_b32_e32 v28, 2, v26
	v_mov_b32_e32 v29, v1
	v_or_b32_e32 v30, 0x3000, v6
	v_lshlrev_b32_e32 v36, 2, v34
	v_mov_b32_e32 v37, v1
	v_lshl_add_u64 v[8:9], v[2:3], 0, v[8:9]
	v_lshl_add_u64 v[12:13], v[2:3], 0, v[12:13]
	v_lshl_add_u64 v[16:17], v[2:3], 0, v[16:17]
	v_lshl_add_u64 v[20:21], v[2:3], 0, v[20:21]
	v_lshlrev_b32_e32 v24, 2, v22
	v_mov_b32_e32 v25, v1
	v_lshl_add_u64 v[28:29], v[2:3], 0, v[28:29]
	s_waitcnt lgkmcnt(0)
	v_lshlrev_b32_e32 v32, 2, v30
	v_mov_b32_e32 v33, v1
	v_lshl_add_u64 v[36:37], v[2:3], 0, v[36:37]
	v_lshl_add_u64 v[24:25], v[2:3], 0, v[24:25]
	v_lshl_add_u64 v[32:33], v[2:3], 0, v[32:33]
	global_load_dword v7, v[8:9], off nt
	s_nop 0
	global_load_dword v9, v[12:13], off nt
	global_load_dword v11, v[16:17], off nt
	s_nop 0
	global_load_dword v13, v[20:21], off nt
	global_load_dword v15, v[24:25], off nt
	global_load_dword v17, v[28:29], off nt
	global_load_dword v19, v[32:33], off nt
	s_nop 0
	global_load_dword v36, v[36:37], off nt
	v_or_b32_e32 v20, 0x4000, v6
	v_or_b32_e32 v28, 0x4800, v6
	v_lshlrev_b32_e32 v24, 2, v20
	v_mov_b32_e32 v25, v1
	v_lshlrev_b32_e32 v32, 2, v28
	v_mov_b32_e32 v33, v1
	v_or_b32_e32 v42, 0x5000, v6
	v_or_b32_e32 v44, 0x5800, v6
	v_or_b32_e32 v46, 0x6000, v6
	v_or_b32_e32 v50, 0x6800, v6
	v_or_b32_e32 v54, 0x7000, v6
	v_or_b32_e32 v58, 0x7800, v6
	v_lshl_add_u64 v[24:25], v[2:3], 0, v[24:25]
	v_lshl_add_u64 v[32:33], v[2:3], 0, v[32:33]
	v_lshlrev_b32_e32 v38, 2, v42
	v_mov_b32_e32 v39, v1
	v_lshlrev_b32_e32 v40, 2, v44
	v_mov_b32_e32 v41, v1
	v_lshlrev_b32_e32 v48, 2, v46
	v_mov_b32_e32 v49, v1
	v_lshlrev_b32_e32 v52, 2, v50
	v_mov_b32_e32 v53, v1
	v_lshlrev_b32_e32 v56, 2, v54
	v_mov_b32_e32 v57, v1
	v_lshlrev_b32_e32 v60, 2, v58
	v_mov_b32_e32 v61, v1
	v_lshl_add_u64 v[38:39], v[2:3], 0, v[38:39]
	v_lshl_add_u64 v[40:41], v[2:3], 0, v[40:41]
	v_lshl_add_u64 v[48:49], v[2:3], 0, v[48:49]
	v_lshl_add_u64 v[52:53], v[2:3], 0, v[52:53]
	v_lshl_add_u64 v[56:57], v[2:3], 0, v[56:57]
	v_lshl_add_u64 v[2:3], v[2:3], 0, v[60:61]
	global_load_dword v21, v[24:25], off nt
	global_load_dword v23, v[32:33], off nt
	s_nop 0
	global_load_dword v25, v[38:39], off nt
	global_load_dword v27, v[40:41], off nt
	global_load_dword v29, v[48:49], off nt
	global_load_dword v31, v[52:53], off nt
	global_load_dword v33, v[56:57], off nt
	global_load_dword v35, v[2:3], off nt
	v_bfe_u32 v37, v4, 3, 5
	v_lshlrev_b32_e32 v4, 3, v4
	v_and_b32_e32 v8, 56, v4
	v_lshlrev_b32_e32 v4, 1, v8
	v_mul_u32_u24_e32 v8, 0x41, v8
	v_lshlrev_b32_e32 v8, 2, v8
	v_lshlrev_b32_e32 v12, 2, v37
	v_mov_b32_e32 v5, v1
	v_add3_u32 v39, s33, v8, v12
	v_mul_u32_u24_e32 v8, 0x104, v43
	v_lshl_add_u64 v[2:3], s[20:21], 0, v[0:1]
	v_lshl_add_u64 v[4:5], s[0:1], 0, v[4:5]
	v_or_b32_e32 v38, 32, v37
	v_add3_u32 v40, s33, v8, v0
	v_lshlrev_b32_e32 v0, 2, v6
	v_lshlrev_b32_e32 v6, 2, v10
	v_lshlrev_b32_e32 v8, 2, v14
	v_lshlrev_b32_e32 v10, 2, v18
	v_lshlrev_b32_e32 v12, 2, v22
	v_lshlrev_b32_e32 v14, 2, v26
	v_lshlrev_b32_e32 v16, 2, v30
	v_lshlrev_b32_e32 v18, 2, v34
	v_lshlrev_b32_e32 v20, 2, v20
	v_lshlrev_b32_e32 v22, 2, v28
	v_lshlrev_b32_e32 v24, 2, v42
	v_lshlrev_b32_e32 v26, 2, v44
	v_lshlrev_b32_e32 v28, 2, v46
	v_lshlrev_b32_e32 v30, 2, v50
	v_lshlrev_b32_e32 v32, 2, v54
	v_lshlrev_b32_e32 v34, 2, v58
	v_readlane_b32 s6, v254, 45
	v_readlane_b32 s7, v254, 46
	v_readlane_b32 s8, v254, 47
	v_readlane_b32 s9, v254, 48
	v_readlane_b32 s10, v254, 49
	v_readlane_b32 s11, v254, 50
	v_readlane_b32 s12, v254, 51
	v_readlane_b32 s13, v254, 52
	v_readlane_b32 s14, v254, 53
	v_readlane_b32 s15, v254, 54
	v_readlane_b32 s16, v254, 55
	v_readlane_b32 s17, v254, 56
	v_readlane_b32 s18, v254, 57
	v_readlane_b32 s19, v254, 58
	s_branch .LBB0_25

.LBB0_27:
	v_mov_b32_e32 v4, v196
	v_readlane_b32 vcc_hi, v255, 44
	s_sub_i32 s20, s2, vcc_hi
	s_cmp_lt_i32 s20, 0
	s_cselect_b32 vcc_lo, s34, 0
	s_add_i32 s20, s20, vcc_lo
	s_add_i32 vcc_hi, vcc_hi, 4
	s_cmp_ge_u32 vcc_hi, s34
	s_cselect_b32 vcc_lo, s34, 0
	s_sub_i32 vcc_hi, vcc_hi, vcc_lo
	s_nop 0
	v_writelane_b32 v255, vcc_hi, 44
	v_mov_b32_e32 v0, v196
	s_lshl_b32 s20, s20, 1
	v_readfirstlane_b32 s21, v0
	s_ashr_i32 s21, s21, 8
	v_mov_b32_e32 v0, v196
	s_add_i32 s21, s21, s20
	s_nop 0
	v_readfirstlane_b32 s20, v0
	s_ashr_i32 s20, s20, 8
	s_sub_i32 s23, s21, s20
	s_cmp_gt_i32 s23, 7
	s_cbranch_scc1 .LBB0_21
	v_readlane_b32 s4, v254, 43
	s_lshl_b64 s[20:21], s[30:31], 2
	v_readlane_b32 s8, v254, 47
	v_mov_b32_e32 v0, v196
	v_readlane_b32 s9, v254, 48
	s_add_u32 s20, s8, s20
	s_addc_u32 s21, s9, s21
	v_readfirstlane_b32 s24, v0
	s_ashr_i32 s24, s24, 8
	s_add_i32 s24, s24, s23
	s_min_i32 s24, s24, 7
	s_lshl_b32 s24, s24, 6
	s_ashr_i32 s25, s24, 31
	v_bfe_u32 v43, v4, 6, 2
	s_lshl_b64 s[24:25], s[24:25], 2
	s_add_u32 s24, s20, s24
	v_lshlrev_b32_e32 v0, 2, v4
	v_lshlrev_b32_e32 v6, 9, v43
	s_addc_u32 s25, s21, s25
	v_and_b32_e32 v0, 0xfc, v0
	s_waitcnt vmcnt(15)
	v_or_b32_e32 v10, 0x800, v6
	v_or_b32_e32 v14, 0x1000, v6
	s_waitcnt vmcnt(9)
	v_or_b32_e32 v18, 0x1800, v6
	s_waitcnt vmcnt(2)
	v_or_b32_e32 v26, 0x2800, v6
	v_or_b32_e32 v34, 0x3800, v6
	v_lshl_add_u64 v[2:3], s[24:25], 0, v[0:1]
	s_waitcnt vmcnt(1)
	v_lshlrev_b32_e32 v8, 11, v43
	s_waitcnt vmcnt(16)
	v_mov_b32_e32 v9, v1
	v_lshlrev_b32_e32 v12, 2, v10
	s_waitcnt vmcnt(14)
	v_mov_b32_e32 v13, v1
	s_waitcnt vmcnt(0)
	v_lshlrev_b32_e32 v16, 2, v14
	s_waitcnt vmcnt(12)
	v_mov_b32_e32 v17, v1
	v_lshlrev_b32_e32 v20, 2, v18
	s_waitcnt vmcnt(9)
	v_mov_b32_e32 v21, v1
	v_or_b32_e32 v22, 0x2000, v6
	v_lshlrev_b32_e32 v28, 2, v26
	s_waitcnt vmcnt(5)
	v_mov_b32_e32 v29, v1
	v_or_b32_e32 v30, 0x3000, v6
	v_lshlrev_b32_e32 v36, 2, v34
	v_mov_b32_e32 v37, v1
	v_lshl_add_u64 v[8:9], v[2:3], 0, v[8:9]
	v_lshl_add_u64 v[12:13], v[2:3], 0, v[12:13]
	v_lshl_add_u64 v[16:17], v[2:3], 0, v[16:17]
	v_lshl_add_u64 v[20:21], v[2:3], 0, v[20:21]
	v_lshlrev_b32_e32 v24, 2, v22
	v_mov_b32_e32 v25, v1
	v_lshl_add_u64 v[28:29], v[2:3], 0, v[28:29]
	s_waitcnt lgkmcnt(0)
	v_lshlrev_b32_e32 v32, 2, v30
	s_waitcnt vmcnt(3)
	v_mov_b32_e32 v33, v1
	v_lshl_add_u64 v[36:37], v[2:3], 0, v[36:37]
	v_lshl_add_u64 v[24:25], v[2:3], 0, v[24:25]
	v_lshl_add_u64 v[32:33], v[2:3], 0, v[32:33]
	global_load_dword v7, v[8:9], off nt
	s_nop 0
	global_load_dword v9, v[12:13], off nt
	global_load_dword v11, v[16:17], off nt
	s_nop 0
	global_load_dword v13, v[20:21], off nt
	global_load_dword v15, v[24:25], off nt
	global_load_dword v17, v[28:29], off nt
	global_load_dword v19, v[32:33], off nt
	s_nop 0
	global_load_dword v36, v[36:37], off nt
	v_or_b32_e32 v20, 0x4000, v6
	v_or_b32_e32 v28, 0x4800, v6
	v_lshlrev_b32_e32 v24, 2, v20
	v_mov_b32_e32 v25, v1
	v_lshlrev_b32_e32 v32, 2, v28
	v_mov_b32_e32 v33, v1
	v_or_b32_e32 v42, 0x5000, v6
	v_or_b32_e32 v44, 0x5800, v6
	v_or_b32_e32 v46, 0x6000, v6
	v_or_b32_e32 v50, 0x6800, v6
	v_or_b32_e32 v54, 0x7000, v6
	v_or_b32_e32 v58, 0x7800, v6
	v_lshl_add_u64 v[24:25], v[2:3], 0, v[24:25]
	v_lshl_add_u64 v[32:33], v[2:3], 0, v[32:33]
	v_lshlrev_b32_e32 v38, 2, v42
	v_mov_b32_e32 v39, v1
	v_lshlrev_b32_e32 v40, 2, v44
	v_mov_b32_e32 v41, v1
	v_lshlrev_b32_e32 v48, 2, v46
	v_mov_b32_e32 v49, v1
	v_lshlrev_b32_e32 v52, 2, v50
	v_mov_b32_e32 v53, v1
	v_lshlrev_b32_e32 v56, 2, v54
	v_mov_b32_e32 v57, v1
	v_lshlrev_b32_e32 v60, 2, v58
	v_mov_b32_e32 v61, v1
	v_lshl_add_u64 v[38:39], v[2:3], 0, v[38:39]
	v_lshl_add_u64 v[40:41], v[2:3], 0, v[40:41]
	v_lshl_add_u64 v[48:49], v[2:3], 0, v[48:49]
	v_lshl_add_u64 v[52:53], v[2:3], 0, v[52:53]
	v_lshl_add_u64 v[56:57], v[2:3], 0, v[56:57]
	v_lshl_add_u64 v[2:3], v[2:3], 0, v[60:61]
	global_load_dword v21, v[24:25], off nt
	global_load_dword v23, v[32:33], off nt
	s_nop 0
	global_load_dword v25, v[38:39], off nt
	global_load_dword v27, v[40:41], off nt
	global_load_dword v29, v[48:49], off nt
	global_load_dword v31, v[52:53], off nt
	global_load_dword v33, v[56:57], off nt
	global_load_dword v35, v[2:3], off nt
	v_bfe_u32 v37, v4, 3, 5
	v_lshlrev_b32_e32 v4, 3, v4
	v_and_b32_e32 v8, 56, v4
	v_lshlrev_b32_e32 v4, 1, v8
	v_mul_u32_u24_e32 v8, 0x41, v8
	v_mov_b32_e32 v5, v1
	v_lshlrev_b32_e32 v8, 2, v8
	v_lshlrev_b32_e32 v12, 2, v37
	v_lshl_add_u64 v[4:5], s[0:1], 0, v[4:5]
	s_mov_b64 s[0:1], 0x80080
	v_add3_u32 v39, s33, v8, v12
	v_mul_u32_u24_e32 v8, 0x104, v43
	v_lshl_add_u64 v[2:3], s[20:21], 0, v[0:1]
	v_lshl_add_u64 v[4:5], v[4:5], 0, s[0:1]
	v_or_b32_e32 v38, 32, v37
	v_add3_u32 v40, s33, v8, v0
	v_lshlrev_b32_e32 v0, 2, v6
	v_lshlrev_b32_e32 v6, 2, v10
	v_lshlrev_b32_e32 v8, 2, v14
	v_lshlrev_b32_e32 v10, 2, v18
	v_lshlrev_b32_e32 v12, 2, v22
	v_lshlrev_b32_e32 v14, 2, v26
	v_lshlrev_b32_e32 v16, 2, v30
	v_lshlrev_b32_e32 v18, 2, v34
	v_lshlrev_b32_e32 v20, 2, v20
	v_lshlrev_b32_e32 v22, 2, v28
	v_lshlrev_b32_e32 v24, 2, v42
	v_lshlrev_b32_e32 v26, 2, v44
	v_lshlrev_b32_e32 v28, 2, v46
	v_lshlrev_b32_e32 v30, 2, v50
	v_lshlrev_b32_e32 v32, 2, v54
	v_lshlrev_b32_e32 v34, 2, v58
	v_readlane_b32 s5, v254, 44
	v_readlane_b32 s6, v254, 45
	v_readlane_b32 s7, v254, 46
	v_readlane_b32 s10, v254, 49
	v_readlane_b32 s11, v254, 50
	v_readlane_b32 s12, v254, 51
	v_readlane_b32 s13, v254, 52
	v_readlane_b32 s14, v254, 53
	v_readlane_b32 s15, v254, 54
	v_readlane_b32 s16, v254, 55
	v_readlane_b32 s17, v254, 56
	v_readlane_b32 s18, v254, 57
	v_readlane_b32 s19, v254, 58
	s_branch .LBB0_30

.LBB0_32:
	v_mov_b32_e32 v4, v196
	v_readlane_b32 vcc_hi, v255, 44
	s_sub_i32 s0, s2, vcc_hi
	s_cmp_lt_i32 s0, 0
	s_cselect_b32 vcc_lo, s34, 0
	s_add_i32 s0, s0, vcc_lo
	s_add_i32 vcc_hi, vcc_hi, 8
	s_cmp_ge_u32 vcc_hi, s34
	s_cselect_b32 vcc_lo, s34, 0
	s_sub_i32 vcc_hi, vcc_hi, vcc_lo
	s_nop 0
	v_writelane_b32 v255, vcc_hi, 44
	v_mov_b32_e32 v0, v196
	s_lshl_b32 s0, s0, 1
	v_readfirstlane_b32 s1, v0
	s_ashr_i32 s1, s1, 8
	v_mov_b32_e32 v0, v196
	s_add_i32 s1, s1, s0
	s_nop 0
	v_readfirstlane_b32 s0, v0
	s_ashr_i32 s0, s0, 8
	s_sub_i32 s20, s1, s0
	s_cmp_gt_i32 s20, 15
	s_cbranch_scc1 .LBB0_19
	s_mov_b32 s45, s31
	v_readlane_b32 s4, v254, 43
	s_lshl_b64 s[0:1], s[44:45], 18
	v_readlane_b32 s10, v254, 49
	v_mov_b32_e32 v0, v196
	v_readlane_b32 s11, v254, 50
	s_add_u32 s0, s10, s0
	s_addc_u32 s1, s11, s1
	v_readfirstlane_b32 s21, v0
	s_ashr_i32 s21, s21, 8
	s_add_i32 s21, s21, s20
	s_min_i32 s21, s21, 15
	s_lshr_b32 s22, s21, 31
	s_add_i32 s22, s21, s22
	s_and_b32 s23, s22, 0x3fffffe
	v_bfe_u32 v6, v4, 6, 2
	s_sub_i32 s21, s21, s23
	v_lshl_or_b32 v2, s21, 6, v6
	s_lshl_b32 s21, s22, 5
	s_and_b32 s22, s21, 0xffffffc0
	s_ashr_i32 s23, s22, 31
	s_lshl_b64 s[22:23], s[22:23], 2
	s_add_u32 s22, s0, s22
	v_lshlrev_b32_e32 v0, 2, v4
	s_waitcnt vmcnt(15)
	v_or_b32_e32 v10, 4, v2
	s_waitcnt vmcnt(14)
	v_or_b32_e32 v12, 8, v2
	v_or_b32_e32 v14, 12, v2
	s_waitcnt vmcnt(0)
	v_or_b32_e32 v16, 16, v2
	v_or_b32_e32 v20, 20, v2
	v_or_b32_e32 v22, 24, v2
	v_or_b32_e32 v24, 28, v2
	s_addc_u32 s23, s1, s23
	v_and_b32_e32 v0, 0xfc, v0
	v_ashrrev_i32_e32 v3, 31, v2
	s_waitcnt vmcnt(15)
	v_ashrrev_i32_e32 v11, 31, v10
	s_waitcnt vmcnt(14)
	v_ashrrev_i32_e32 v13, 31, v12
	s_waitcnt vmcnt(13)
	v_ashrrev_i32_e32 v15, 31, v14
	s_waitcnt vmcnt(12)
	v_ashrrev_i32_e32 v17, 31, v16
	s_waitcnt vmcnt(9)
	v_ashrrev_i32_e32 v21, 31, v20
	s_waitcnt vmcnt(8) lgkmcnt(4)
	v_ashrrev_i32_e32 v23, 31, v22
	s_waitcnt vmcnt(7)
	v_ashrrev_i32_e32 v25, 31, v24
	v_lshl_add_u64 v[18:19], s[22:23], 0, v[0:1]
	v_lshlrev_b64 v[8:9], 11, v[2:3]
	v_lshlrev_b64 v[10:11], 11, v[10:11]
	v_lshlrev_b64 v[12:13], 11, v[12:13]
	v_lshlrev_b64 v[14:15], 11, v[14:15]
	v_lshlrev_b64 v[16:17], 11, v[16:17]
	v_lshlrev_b64 v[20:21], 11, v[20:21]
	v_lshlrev_b64 v[22:23], 11, v[22:23]
	v_lshlrev_b64 v[24:25], 11, v[24:25]
	v_lshl_add_u64 v[8:9], v[18:19], 0, v[8:9]
	v_lshl_add_u64 v[10:11], v[18:19], 0, v[10:11]
	v_lshl_add_u64 v[12:13], v[18:19], 0, v[12:13]
	v_lshl_add_u64 v[14:15], v[18:19], 0, v[14:15]
	v_lshl_add_u64 v[16:17], v[18:19], 0, v[16:17]
	v_lshl_add_u64 v[20:21], v[18:19], 0, v[20:21]
	v_lshl_add_u64 v[22:23], v[18:19], 0, v[22:23]
	v_lshl_add_u64 v[24:25], v[18:19], 0, v[24:25]
	global_load_dword v8, v[8:9], off nt
	s_nop 0
	global_load_dword v9, v[10:11], off nt
	s_nop 0
	global_load_dword v10, v[12:13], off nt
	s_nop 0
	global_load_dword v12, v[14:15], off nt
	global_load_dword v13, v[16:17], off nt
	s_nop 0
	global_load_dword v15, v[20:21], off nt
	global_load_dword v16, v[22:23], off nt
	global_load_dword v17, v[24:25], off nt
	v_or_b32_e32 v20, 32, v2
	v_or_b32_e32 v22, 36, v2
	v_or_b32_e32 v24, 40, v2
	v_ashrrev_i32_e32 v21, 31, v20
	v_ashrrev_i32_e32 v23, 31, v22
	v_ashrrev_i32_e32 v25, 31, v24
	v_or_b32_e32 v26, 44, v2
	v_or_b32_e32 v28, 48, v2
	v_or_b32_e32 v30, 52, v2
	s_waitcnt lgkmcnt(0)
	v_or_b32_e32 v32, 56, v2
	v_or_b32_e32 v2, 60, v2
	v_lshlrev_b64 v[20:21], 11, v[20:21]
	v_lshlrev_b64 v[22:23], 11, v[22:23]
	v_lshlrev_b64 v[24:25], 11, v[24:25]
	s_waitcnt vmcnt(14)
	v_ashrrev_i32_e32 v27, 31, v26
	s_waitcnt vmcnt(13)
	v_ashrrev_i32_e32 v29, 31, v28
	s_waitcnt vmcnt(12)
	v_ashrrev_i32_e32 v31, 31, v30
	s_waitcnt vmcnt(11)
	v_ashrrev_i32_e32 v33, 31, v32
	v_ashrrev_i32_e32 v3, 31, v2
	v_lshl_add_u64 v[20:21], v[18:19], 0, v[20:21]
	v_lshl_add_u64 v[22:23], v[18:19], 0, v[22:23]
	v_lshl_add_u64 v[24:25], v[18:19], 0, v[24:25]
	v_lshlrev_b64 v[26:27], 11, v[26:27]
	v_lshlrev_b64 v[28:29], 11, v[28:29]
	v_lshlrev_b64 v[30:31], 11, v[30:31]
	v_lshlrev_b64 v[32:33], 11, v[32:33]
	v_lshlrev_b64 v[2:3], 11, v[2:3]
	v_lshl_add_u64 v[26:27], v[18:19], 0, v[26:27]
	v_lshl_add_u64 v[28:29], v[18:19], 0, v[28:29]
	v_lshl_add_u64 v[30:31], v[18:19], 0, v[30:31]
	v_lshl_add_u64 v[32:33], v[18:19], 0, v[32:33]
	v_lshl_add_u64 v[2:3], v[18:19], 0, v[2:3]
	global_load_dword v18, v[20:21], off nt
	global_load_dword v19, v[22:23], off nt
	s_nop 0
	global_load_dword v20, v[24:25], off nt
	global_load_dword v21, v[26:27], off nt
	global_load_dword v22, v[28:29], off nt
	global_load_dword v23, v[30:31], off nt
	s_nop 0
	global_load_dword v24, v[32:33], off nt
	global_load_dword v25, v[2:3], off nt
	v_bfe_u32 v7, v4, 3, 5
	v_lshlrev_b32_e32 v4, 3, v4
	v_and_b32_e32 v11, 56, v4
	v_mul_u32_u24_e32 v14, 0x41, v11
	v_lshlrev_b32_e32 v4, 1, v11
	v_mov_b32_e32 v5, v1
	v_lshlrev_b32_e32 v14, 2, v14
	v_lshlrev_b32_e32 v26, 2, v7
	v_lshl_add_u64 v[2:3], s[0:1], 0, v[0:1]
	v_lshl_add_u64 v[4:5], s[42:43], 0, v[4:5]
	s_mov_b64 s[0:1], 0x100100
	v_add3_u32 v14, s33, v14, v26
	v_mul_u32_u24_e32 v26, 0x104, v6
	v_lshl_add_u64 v[4:5], v[4:5], 0, s[0:1]
	v_or_b32_e32 v11, 32, v7
	v_add3_u32 v0, s33, v26, v0
	v_readlane_b32 s5, v254, 44
	v_readlane_b32 s6, v254, 45
	v_readlane_b32 s7, v254, 46
	v_readlane_b32 s8, v254, 47
	v_readlane_b32 s9, v254, 48
	v_readlane_b32 s12, v254, 51
	v_readlane_b32 s13, v254, 52
	v_readlane_b32 s14, v254, 53
	v_readlane_b32 s15, v254, 54
	v_readlane_b32 s16, v254, 55
	v_readlane_b32 s17, v254, 56
	v_readlane_b32 s18, v254, 57
	v_readlane_b32 s19, v254, 58
	s_branch .LBB0_35
